# GEMM tile loop: drop the compiler's vmcnt(0) flush at the tile-loop head of the first ffn_up and first pool GEMM (it waited for the epilogue's store acknowledgements; the K loop's counted waits alread
# baseline (speedup 1.0000x reference)
; template <class Epi>
; __device__ __forceinline__ void gemm_phase(LAS unsigned char* lds, const Gemm g, const StaticOrder& S, const Epi& E) {
;     ...
;         const bool has_next = S.next(ui + 1, nxt);
;         const char* nA = has_next ? (const char*)g.A + (size_t)rowstart(nxt.pm) * rstepA + (size_t)nxt.pn * gstepA : cA; const char* nB = has_next ? (const char*)g.Bt + (size_t)nxt.pn * tstepB : cB;
;     ...
; #pragma unroll
;         for (int a = 0; a < 2; ++a)
; #pragma unroll
;             for (int b = 0; b < 2; ++b)
; #pragma unroll
;                 for (int m = 0; m < 4; ++m)
; #pragma unroll
;                     for (int n = 0; n < 2; ++n) acc[a][b][m][n] = (f32x4){0.f, 0.f, 0.f, 0.f};
.LBB0_149:
	s_lshl_b64 s[0:1], s[96:97], 17
	s_add_u32 s64, s12, s0
	s_addc_u32 s65, s13, s1
	s_and_b64 s[0:1], s[6:7], exec
	v_mov_b32_e32 v0, 0
	s_cselect_b32 s41, s65, s9
	s_cselect_b32 s61, s64, s8
	s_mov_b32 s42, 0
	s_mov_b64 s[0:1], -1
	s_mov_b64 s[36:37], 0
	s_waitcnt lgkmcnt(0)
	v_mov_b32_e32 v1, v0
	v_mov_b32_e32 v2, v0
	v_mov_b32_e32 v3, v0
	v_mov_b32_e32 v4, v0
	v_mov_b32_e32 v5, v0
	v_mov_b32_e32 v6, v0
	v_mov_b32_e32 v7, v0
	v_mov_b32_e32 v16, v0
	v_mov_b32_e32 v17, v0
	v_mov_b32_e32 v18, v0
	v_mov_b32_e32 v19, v0
	v_mov_b32_e32 v20, v0
	v_mov_b32_e32 v21, v0
	v_mov_b32_e32 v22, v0
	v_mov_b32_e32 v23, v0
	v_mov_b32_e32 v32, v0
	v_mov_b32_e32 v33, v0
	v_mov_b32_e32 v34, v0
	v_mov_b32_e32 v35, v0
	v_mov_b32_e32 v36, v0
	v_mov_b32_e32 v37, v0
	v_mov_b32_e32 v38, v0
	v_mov_b32_e32 v39, v0
	v_mov_b32_e32 v80, v0
	v_mov_b32_e32 v81, v0
	v_mov_b32_e32 v82, v0
	v_mov_b32_e32 v83, v0
	v_mov_b32_e32 v84, v0
	v_mov_b32_e32 v85, v0
	v_mov_b32_e32 v86, v0
	v_mov_b32_e32 v87, v0
	v_mov_b32_e32 v8, v0
	v_mov_b32_e32 v9, v0
	v_mov_b32_e32 v10, v0
	v_mov_b32_e32 v11, v0
	v_mov_b32_e32 v12, v0
	v_mov_b32_e32 v13, v0
	v_mov_b32_e32 v14, v0
	v_mov_b32_e32 v15, v0
	v_mov_b32_e32 v24, v0
	v_mov_b32_e32 v25, v0
	v_mov_b32_e32 v26, v0
	v_mov_b32_e32 v27, v0
	v_mov_b32_e32 v28, v0
	v_mov_b32_e32 v29, v0
	v_mov_b32_e32 v30, v0
	v_mov_b32_e32 v31, v0
	v_mov_b32_e32 v56, v0
	v_mov_b32_e32 v57, v0
	v_mov_b32_e32 v58, v0
	v_mov_b32_e32 v59, v0
	v_mov_b32_e32 v64, v0
	v_mov_b32_e32 v65, v0
	v_mov_b32_e32 v66, v0
	v_mov_b32_e32 v67, v0
	v_mov_b32_e32 v88, v0
	v_mov_b32_e32 v89, v0
	v_mov_b32_e32 v90, v0
	v_mov_b32_e32 v91, v0
	v_mov_b32_e32 v92, v0
	v_mov_b32_e32 v93, v0
	v_mov_b32_e32 v94, v0
	v_mov_b32_e32 v95, v0
	v_mov_b32_e32 v96, v0
	v_mov_b32_e32 v97, v0
	v_mov_b32_e32 v98, v0
	v_mov_b32_e32 v99, v0
	v_mov_b32_e32 v100, v0
	v_mov_b32_e32 v101, v0
	v_mov_b32_e32 v102, v0
	v_mov_b32_e32 v103, v0
	v_mov_b32_e32 v112, v0
	v_mov_b32_e32 v113, v0
	v_mov_b32_e32 v114, v0
	v_mov_b32_e32 v115, v0
	v_mov_b32_e32 v116, v0
	v_mov_b32_e32 v117, v0
	v_mov_b32_e32 v118, v0
	v_mov_b32_e32 v119, v0
	v_mov_b32_e32 v128, v0
	v_mov_b32_e32 v129, v0
	v_mov_b32_e32 v130, v0
	v_mov_b32_e32 v131, v0
	v_mov_b32_e32 v132, v0
	v_mov_b32_e32 v133, v0
	v_mov_b32_e32 v134, v0
	v_mov_b32_e32 v135, v0
	v_mov_b32_e32 v144, v0
	v_mov_b32_e32 v145, v0
	v_mov_b32_e32 v146, v0
	v_mov_b32_e32 v147, v0
	v_mov_b32_e32 v148, v0
	v_mov_b32_e32 v149, v0
	v_mov_b32_e32 v150, v0
	v_mov_b32_e32 v151, v0
	v_mov_b32_e32 v104, v0
	v_mov_b32_e32 v105, v0
	v_mov_b32_e32 v106, v0
	v_mov_b32_e32 v107, v0
	v_mov_b32_e32 v108, v0
	v_mov_b32_e32 v109, v0
	v_mov_b32_e32 v110, v0
	v_mov_b32_e32 v111, v0
	v_mov_b32_e32 v120, v0
	v_mov_b32_e32 v121, v0
	v_mov_b32_e32 v122, v0
	v_mov_b32_e32 v123, v0
	v_mov_b32_e32 v124, v0
	v_mov_b32_e32 v125, v0
	v_mov_b32_e32 v126, v0
	v_mov_b32_e32 v127, v0
	v_mov_b32_e32 v136, v0
	v_mov_b32_e32 v137, v0
	v_mov_b32_e32 v138, v0
	v_mov_b32_e32 v139, v0
	v_mov_b32_e32 v140, v0
	v_mov_b32_e32 v141, v0
	v_mov_b32_e32 v142, v0
	v_mov_b32_e32 v143, v0
	v_mov_b32_e32 v152, v0
	v_mov_b32_e32 v153, v0
	v_mov_b32_e32 v154, v0
	v_mov_b32_e32 v155, v0
	v_mov_b32_e32 v156, v0
	v_mov_b32_e32 v157, v0
	v_mov_b32_e32 v158, v0
	v_mov_b32_e32 v159, v0

; template <class Epi>
; __device__ __forceinline__ void gemm_phase(LAS unsigned char* lds, const Gemm g, const StaticOrder& S, const Epi& E) {
;     ...
;         const bool has_next = S.next(ui + 1, nxt);
;         const char* nA = has_next ? (const char*)g.A + (size_t)rowstart(nxt.pm) * rstepA + (size_t)nxt.pn * gstepA : cA; const char* nB = has_next ? (const char*)g.Bt + (size_t)nxt.pn * tstepB : cB;
;     ...
; #pragma unroll
;         for (int a = 0; a < 2; ++a)
; #pragma unroll
;             for (int b = 0; b < 2; ++b)
; #pragma unroll
;                 for (int m = 0; m < 4; ++m)
; #pragma unroll
;                     for (int n = 0; n < 2; ++n) acc[a][b][m][n] = (f32x4){0.f, 0.f, 0.f, 0.f};
.LBB0_254:
	s_ashr_i32 s17, s16, 31
	s_lshl_b64 s[28:29], s[16:17], 19
	s_add_u32 s28, s84, s28
	s_addc_u32 s29, s85, s29
	s_and_b64 s[0:1], s[0:1], exec
	s_cselect_b32 s7, s29, s37
	s_cselect_b32 s17, s28, s36
	s_add_u32 s0, s38, 0x40080
	s_addc_u32 s1, s39, 0
	s_add_u32 s59, s36, 0x100
	v_mov_b32_e32 v0, 0
	s_addc_u32 s60, s37, 0
	s_mov_b32 s61, -2
	v_mov_b32_e32 v1, v0
	v_mov_b32_e32 v2, v0
	v_mov_b32_e32 v3, v0
	v_mov_b32_e32 v8, v0
	v_mov_b32_e32 v9, v0
	v_mov_b32_e32 v10, v0
	v_mov_b32_e32 v11, v0
	v_mov_b32_e32 v16, v0
	v_mov_b32_e32 v17, v0
	v_mov_b32_e32 v18, v0
	v_mov_b32_e32 v19, v0
	v_mov_b32_e32 v24, v0
	v_mov_b32_e32 v25, v0
	v_mov_b32_e32 v26, v0
	v_mov_b32_e32 v27, v0
	v_mov_b32_e32 v32, v0
	v_mov_b32_e32 v33, v0
	v_mov_b32_e32 v34, v0
	v_mov_b32_e32 v35, v0
	v_mov_b32_e32 v40, v0
	v_mov_b32_e32 v41, v0
	v_mov_b32_e32 v42, v0
	v_mov_b32_e32 v43, v0
	v_mov_b32_e32 v48, v0
	v_mov_b32_e32 v49, v0
	v_mov_b32_e32 v50, v0
	v_mov_b32_e32 v51, v0
	v_mov_b32_e32 v56, v0
	v_mov_b32_e32 v57, v0
	v_mov_b32_e32 v58, v0
	v_mov_b32_e32 v59, v0
	v_mov_b32_e32 v4, v0
	v_mov_b32_e32 v5, v0
	v_mov_b32_e32 v6, v0
	v_mov_b32_e32 v7, v0
	v_mov_b32_e32 v12, v0
	v_mov_b32_e32 v13, v0
	v_mov_b32_e32 v14, v0
	v_mov_b32_e32 v15, v0
	v_mov_b32_e32 v20, v0
	v_mov_b32_e32 v21, v0
	v_mov_b32_e32 v22, v0
	v_mov_b32_e32 v23, v0
	v_mov_b32_e32 v28, v0
	v_mov_b32_e32 v29, v0
	v_mov_b32_e32 v30, v0
	v_mov_b32_e32 v31, v0
	v_mov_b32_e32 v36, v0
	v_mov_b32_e32 v37, v0
	v_mov_b32_e32 v38, v0
	v_mov_b32_e32 v39, v0
	v_mov_b32_e32 v44, v0
	v_mov_b32_e32 v45, v0
	v_mov_b32_e32 v46, v0
	v_mov_b32_e32 v47, v0
	v_mov_b32_e32 v52, v0
	v_mov_b32_e32 v53, v0
	v_mov_b32_e32 v54, v0
	v_mov_b32_e32 v55, v0
	v_mov_b32_e32 v60, v0
	v_mov_b32_e32 v61, v0
	v_mov_b32_e32 v62, v0
	v_mov_b32_e32 v63, v0
	v_mov_b32_e32 v64, v0
	v_mov_b32_e32 v65, v0
	v_mov_b32_e32 v66, v0
	v_mov_b32_e32 v67, v0
	v_mov_b32_e32 v72, v0
	v_mov_b32_e32 v73, v0
	v_mov_b32_e32 v74, v0
	v_mov_b32_e32 v75, v0
	v_mov_b32_e32 v80, v0
	v_mov_b32_e32 v81, v0
	v_mov_b32_e32 v82, v0
	v_mov_b32_e32 v83, v0
	v_mov_b32_e32 v88, v0
	v_mov_b32_e32 v89, v0
	v_mov_b32_e32 v90, v0
	v_mov_b32_e32 v91, v0
	v_mov_b32_e32 v96, v0
	v_mov_b32_e32 v97, v0
	v_mov_b32_e32 v98, v0
	v_mov_b32_e32 v99, v0
	v_mov_b32_e32 v104, v0
	v_mov_b32_e32 v105, v0
	v_mov_b32_e32 v106, v0
	v_mov_b32_e32 v107, v0
	v_mov_b32_e32 v112, v0
	v_mov_b32_e32 v113, v0
	v_mov_b32_e32 v114, v0
	v_mov_b32_e32 v115, v0
	v_mov_b32_e32 v120, v0
	v_mov_b32_e32 v121, v0
	v_mov_b32_e32 v122, v0
	v_mov_b32_e32 v123, v0
	v_mov_b32_e32 v68, v0
	v_mov_b32_e32 v69, v0
	v_mov_b32_e32 v70, v0
	v_mov_b32_e32 v71, v0
	v_mov_b32_e32 v76, v0
	v_mov_b32_e32 v77, v0
	v_mov_b32_e32 v78, v0
	v_mov_b32_e32 v79, v0
	v_mov_b32_e32 v84, v0
	v_mov_b32_e32 v85, v0
	v_mov_b32_e32 v86, v0
	v_mov_b32_e32 v87, v0
	v_mov_b32_e32 v92, v0
	v_mov_b32_e32 v93, v0
	v_mov_b32_e32 v94, v0
	v_mov_b32_e32 v95, v0
	v_mov_b32_e32 v100, v0
	v_mov_b32_e32 v101, v0
	v_mov_b32_e32 v102, v0
	v_mov_b32_e32 v103, v0
	v_mov_b32_e32 v108, v0
	v_mov_b32_e32 v109, v0
	v_mov_b32_e32 v110, v0
	v_mov_b32_e32 v111, v0
	v_mov_b32_e32 v116, v0
	v_mov_b32_e32 v117, v0
	v_mov_b32_e32 v118, v0
	v_mov_b32_e32 v119, v0
	v_mov_b32_e32 v124, v0
	v_mov_b32_e32 v125, v0
	v_mov_b32_e32 v126, v0
	v_mov_b32_e32 v127, v0
